# plain GEMM K-loop restructured as 8-phase ping-pong: waves 4-7 run half a phase behind waves 0-3 (one matrix section, one load section per SIMD at a time), quarter-K-tile LDS-DMA pieces staged 1.5 K-t
# speedup vs baseline: 1.0365x; 1.0365x over previous
; DI int opqv(int x) { asm volatile("" : "+v"(x)); return x; }
;     ...
;   const int drow = lane >> 3, dslot = lane & 7, x7 = (l32 >> 1) & 7;
;   const int tid = opqv(threadIdx.x), lane = tid & 63, w = tid >> 6, wm = w >> 2, wn = w & 3, l32 = lane & 31, hf = lane >> 5;
;   const int nN = N / 256;
;   for (int lt = blockIdx.x >> 3; lt < 16 * nN; lt += gridDim.x >> 3) {
;     int mt, nt; tile_map(lt, 16, nN, 8, 4, mt, nt);
;     const int m0 = mt * 256, n0 = nt * 256;
;     gemm_tile<V>(A + (size_t)m0 * lda, lda, K / 64, nullptr, 0, 0, Wt + (size_t)n0 * ldb, ldb, smem, [&](f32x16(&acc)[2][2], int moff) {
.LBB0_871:
	s_lshl_b32 s29, s20, 4
	v_readlane_b32 s28, v253, 48
	v_readlane_b32 s30, v253, 50
	s_cmp_ge_u32 s28, s29
	s_cbranch_scc1 .LBB0_882
	s_add_u32 s12, s62, s12
	s_addc_u32 s13, s63, s13
	v_readlane_b32 s31, v251, 0
	s_lshr_b32 s34, s20, 3
	s_lshl_b32 s35, s8, 1
	s_lshl_b32 s36, s10, 1
	s_lshr_b32 s51, s50, 1
	s_sub_u32 s51, s51, 1
	s_and_b32 s31, s31, 7
	s_lshl_b32 s31, s31, 4
	v_lshrrev_b32_e32 v240, 6, v182
	v_and_b32_e32 v241, 63, v182
	v_readfirstlane_b32 s15, v240
	v_and_b32_e32 v242, 15, v241
	v_lshrrev_b32_e32 v243, 4, v241
	v_lshrrev_b32_e32 v244, 3, v241
	v_and_b32_e32 v245, 7, v241
	s_lshr_b32 s53, s15, 2
	s_and_b32 s54, s15, 3
	s_lshl_b32 s14, s53, 14
	s_lshl_b32 s55, s54, 11
	s_add_u32 s14, s14, s55
	s_add_u32 s14, s14, 32
	s_lshr_b32 s55, s15, 1
	s_and_b32 s56, s15, 1
	s_lshl_b32 s41, s55, 13
	s_lshl_b32 s57, s56, 11
	s_add_u32 s41, s41, s57
	s_add_u32 s41, s41, 0x8020
	s_lshl_b32 s57, s53, 7
	s_lshl_b32 s58, s54, 4
	s_add_u32 s57, s57, s58
	s_add_u32 s57, s57, 0
	v_add_u32_e32 v247, s57, v244
	v_lshrrev_b32_e32 v246, 1, v244
	v_xor_b32_e32 v246, v245, v246
	v_lshlrev_b32_e32 v246, 4, v246
	v_mad_u32_u24 v220, v247, s35, v246
	s_lshl_b32 s57, s55, 6
	s_lshl_b32 s58, s56, 4
	s_add_u32 s57, s57, s58
	s_add_u32 s57, s57, 0
	v_add_u32_e32 v247, s57, v244
	v_mad_u32_u24 v212, v247, s35, v246
	s_lshl_b32 s57, s53, 7
	s_lshl_b32 s58, s54, 4
	s_add_u32 s57, s57, s58
	s_add_u32 s57, s57, 8
	v_add_u32_e32 v247, s57, v244
	v_lshrrev_b32_e32 v246, 1, v244
	v_add_u32_e32 v246, 4, v246
	v_xor_b32_e32 v246, v245, v246
	v_lshlrev_b32_e32 v246, 4, v246
	v_mad_u32_u24 v221, v247, s35, v246
	s_lshl_b32 s57, s55, 6
	s_lshl_b32 s58, s56, 4
	s_add_u32 s57, s57, s58
	s_add_u32 s57, s57, 8
	v_add_u32_e32 v247, s57, v244
	v_mad_u32_u24 v213, v247, s35, v246
	s_lshl_b32 s57, s53, 7
	s_lshl_b32 s58, s54, 4
	s_add_u32 s57, s57, s58
	s_add_u32 s57, s57, 64
	v_add_u32_e32 v247, s57, v244
	v_lshrrev_b32_e32 v246, 1, v244
	v_xor_b32_e32 v246, v245, v246
	v_lshlrev_b32_e32 v246, 4, v246
	v_mad_u32_u24 v222, v247, s35, v246
	s_lshl_b32 s57, s55, 6
	s_lshl_b32 s58, s56, 4
	s_add_u32 s57, s57, s58
	s_add_u32 s57, s57, 32
	v_add_u32_e32 v247, s57, v244
	v_mad_u32_u24 v214, v247, s35, v246
	s_lshl_b32 s57, s53, 7
	s_lshl_b32 s58, s54, 4
	s_add_u32 s57, s57, s58
	s_add_u32 s57, s57, 72
	v_add_u32_e32 v247, s57, v244
	v_lshrrev_b32_e32 v246, 1, v244
	v_add_u32_e32 v246, 4, v246
	v_xor_b32_e32 v246, v245, v246
	v_lshlrev_b32_e32 v246, 4, v246
	v_mad_u32_u24 v223, v247, s35, v246
	s_lshl_b32 s57, s55, 6
	s_lshl_b32 s58, s56, 4
	s_add_u32 s57, s57, s58
	s_add_u32 s57, s57, 40
	v_add_u32_e32 v247, s57, v244
	v_mad_u32_u24 v215, v247, s35, v246
	v_lshrrev_b32_e32 v246, 1, v242
	s_lshl_b32 s55, s53, 14
	s_add_u32 s55, s55, 32
	s_lshl_b32 s56, s54, 13
	s_add_u32 s56, s56, 0x8020
	v_lshlrev_b32_e32 v247, 7, v242
	v_add_u32_e32 v240, 0, v243
	v_xor_b32_e32 v240, v240, v246
	v_lshl_add_u32 v240, v240, 4, v247
	v_add_u32_e32 v204, s55, v240
	v_add_u32_e32 v208, s56, v240
	v_add_u32_e32 v206, 0x10000, v204
	v_add_u32_e32 v210, 0x10000, v208
	v_add_u32_e32 v240, 4, v243
	v_xor_b32_e32 v240, v240, v246
	v_lshl_add_u32 v240, v240, 4, v247
	v_add_u32_e32 v205, s55, v240
	v_add_u32_e32 v209, s56, v240
	v_add_u32_e32 v207, 0x10000, v205
	v_add_u32_e32 v211, 0x10000, v209
	s_lshl_b32 s40, s15, 11
	s_add_u32 s40, s40, 0x20020
	v_and_b32_e32 v240, 1, v243
	v_lshlrev_b32_e32 v240, 3, v240
	v_add3_u32 v247, v247, v240, s40
	v_lshrrev_b32_e32 v240, 1, v243
	v_xor_b32_e32 v240, v240, v246
	v_mov_b32_e32 v178, v240
	v_xor_b32_e32 v179, 2, v240
	v_xor_b32_e32 v180, 4, v240
	v_xor_b32_e32 v181, 6, v240
	v_lshl_add_u32 v178, v178, 4, v247
	v_lshl_add_u32 v179, v179, 4, v247
	v_lshl_add_u32 v180, v180, 4, v247
	v_lshl_add_u32 v181, v181, 4, v247
	v_lshrrev_b32_e32 v240, 4, v241
	v_xor_b32_e32 v240, v245, v240
	v_lshlrev_b32_e32 v246, 7, v244
	v_add_u32_e32 v246, s40, v246
	v_lshl_add_u32 v194, v240, 4, v246
	v_xor_b32_e32 v240, 4, v240
	v_lshl_add_u32 v188, v240, 4, v246
	v_lshlrev_b32_e32 v195, 4, v245
	v_mad_u32_u24 v195, v244, s36, v195
	s_lshl_b32 s40, s36, 3
	s_lshl_b32 s58, s53, 7
	s_lshl_b32 s59, s54, 7
	s_mov_b32 s27, s28
	s_mov_b32 s26, 0
	s_lshr_b32 s53, s27, 5
	s_and_b32 s54, s27, 31
	s_lshr_b32 s55, s53, s34
	s_lshl_b32 s56, s55, s34
	s_sub_u32 s56, s53, s56
	s_lshl_b32 s55, s55, 3
	s_add_u32 s55, s55, s31
	s_lshr_b32 s57, s54, 2
	s_add_u32 s55, s55, s57
	s_lshl_b32 s56, s56, 2
	s_and_b32 s57, s54, 3
	s_add_u32 s56, s56, s57
	s_lshl_b32 s57, s55, 8
	s_mul_i32 s57, s57, s35
	s_add_u32 s22, s0, s57
	s_addc_u32 s23, s1, 0
	s_lshl_b32 s57, s56, 8
	s_mul_i32 s57, s57, s35
	s_add_u32 s24, s6, s57
	s_addc_u32 s25, s7, 0
	s_add_u32 m0, s41, 0x0
	s_nop 0
	global_load_lds_dwordx4 v212, s[24:25]
	s_add_u32 m0, s41, 0x400
	s_nop 0
	global_load_lds_dwordx4 v213, s[24:25]
	s_add_u32 m0, s14, 0x0
	s_nop 0
	global_load_lds_dwordx4 v220, s[22:23]
	s_add_u32 m0, s14, 0x400
	s_nop 0
	global_load_lds_dwordx4 v221, s[22:23]
	s_add_u32 m0, s41, 0x1000
	s_nop 0
	global_load_lds_dwordx4 v214, s[24:25]
	s_add_u32 m0, s41, 0x1400
	s_nop 0
	global_load_lds_dwordx4 v215, s[24:25]
	s_add_u32 m0, s14, 0x2000
	s_nop 0
	global_load_lds_dwordx4 v222, s[22:23]
	s_add_u32 m0, s14, 0x2400
	s_nop 0
	global_load_lds_dwordx4 v223, s[22:23]
	s_add_u32 s22, s22, 0x80
	s_addc_u32 s23, s23, 0
	s_add_u32 s24, s24, 0x80
	s_addc_u32 s25, s25, 0
	s_add_u32 s26, s26, 1
	s_cmp_eq_u32 s26, s50
	s_cbranch_scc0 .Lgm_cadv_done1
	s_mov_b32 s26, 0
	s_add_u32 s27, s27, s30
	s_cmp_lt_u32 s27, s29
	s_cbranch_scc1 .Lgm_cadv_new1
	s_lshl_b32 s53, s50, 7
	s_sub_u32 s22, s22, s53
	s_subb_u32 s23, s23, 0
	s_sub_u32 s24, s24, s53
	s_subb_u32 s25, s25, 0
	s_branch .Lgm_cadv_done1

; #define RAWBAR() { asm volatile("s_waitcnt vmcnt(0) lgkmcnt(0)" ::: "memory"); __builtin_amdgcn_s_barrier(); }
;     ...
;   if (V != 1) GLDS(0, 0);
;   RAWBAR();
;   for (int kt = 0; kt < nk; kt += 2) {
;     if (V != 1) GLDS(kt + 1, 1);
.Lgm_cadv_done1:
	s_cmp_lt_u32 s15, 4
	s_cbranch_scc1 .Lgm_pp_lead
	s_barrier
.Lgm_pp_lead:
	s_waitcnt vmcnt(4)
	s_barrier
	s_add_u32 m0, s41, 0x10000
	s_nop 0
	global_load_lds_dwordx4 v212, s[24:25]
	s_add_u32 m0, s41, 0x10400
	s_nop 0
	global_load_lds_dwordx4 v213, s[24:25]
	s_add_u32 m0, s14, 0x10000
	s_nop 0
	global_load_lds_dwordx4 v220, s[22:23]
	s_add_u32 m0, s14, 0x10400
	s_nop 0
	global_load_lds_dwordx4 v221, s[22:23]
	s_add_u32 m0, s41, 0x11000
	s_nop 0
	global_load_lds_dwordx4 v214, s[24:25]
	s_add_u32 m0, s41, 0x11400
	s_nop 0
	global_load_lds_dwordx4 v215, s[24:25]
	s_waitcnt vmcnt(6)
	s_barrier
.Lgm_tile:
	ds_read_b128 v[162:165], v208
	ds_read_b128 v[166:169], v209
	ds_read_b128 v[170:173], v208 offset:2048
	ds_read_b128 v[174:177], v209 offset:2048
	s_add_u32 m0, s14, 0x12000
	ds_read_b128 v[128:131], v204
	ds_read_b128 v[132:135], v205
	ds_read_b128 v[136:139], v204 offset:2048
	ds_read_b128 v[140:143], v205 offset:2048
	global_load_lds_dwordx4 v222, s[22:23]
	s_add_u32 m0, s14, 0x12400
	ds_read_b128 v[144:147], v204 offset:4096
	ds_read_b128 v[148:151], v205 offset:4096
	ds_read_b128 v[152:155], v204 offset:6144
	ds_read_b128 v[156:159], v205 offset:6144
	global_load_lds_dwordx4 v223, s[22:23]
	s_add_u32 s22, s22, 0x80
	s_addc_u32 s23, s23, 0
	s_add_u32 s24, s24, 0x80
	s_addc_u32 s25, s25, 0
	s_add_u32 s26, s26, 1
	s_cmp_eq_u32 s26, s50
	s_cbranch_scc0 .Lgm_cadv_done2
	s_mov_b32 s26, 0
	s_add_u32 s27, s27, s30
	s_cmp_lt_u32 s27, s29
	s_cbranch_scc1 .Lgm_cadv_new2
	s_lshl_b32 s53, s50, 7
	s_sub_u32 s22, s22, s53
	s_subb_u32 s23, s23, 0
	s_sub_u32 s24, s24, s53
	s_subb_u32 s25, s25, 0
	s_branch .Lgm_cadv_done2

; #define RAWBAR() { asm volatile("s_waitcnt vmcnt(0) lgkmcnt(0)" ::: "memory"); __builtin_amdgcn_s_barrier(); }
;     ...
;   if (V != 1) GLDS(0, 0);
;   RAWBAR();
;   for (int kt = 0; kt < nk; kt += 2) {
;     if (V != 1) GLDS(kt + 1, 1);
;     if (V != 2) COMPUTE(0);
;     RAWBAR();
;     if (V != 1) if (kt + 2 < nk) GLDS(kt + 2, 0);
;     if (V != 2) COMPUTE(1);
;     RAWBAR();
.Lgm_cadv_done2:
	s_waitcnt lgkmcnt(8)
	s_barrier
	s_waitcnt lgkmcnt(0)
	s_setprio 1
	v_mfma_f32_16x16x32_bf16 v[0:3], v[162:165], v[128:131], 0
	v_mfma_f32_16x16x32_bf16 v[0:3], v[166:169], v[132:135], v[0:3]
	v_mfma_f32_16x16x32_bf16 v[4:7], v[170:173], v[128:131], 0
	v_mfma_f32_16x16x32_bf16 v[4:7], v[174:177], v[132:135], v[4:7]
	v_mfma_f32_16x16x32_bf16 v[16:19], v[162:165], v[136:139], 0
	v_mfma_f32_16x16x32_bf16 v[16:19], v[166:169], v[140:143], v[16:19]
	v_mfma_f32_16x16x32_bf16 v[20:23], v[170:173], v[136:139], 0
	v_mfma_f32_16x16x32_bf16 v[20:23], v[174:177], v[140:143], v[20:23]
	v_mfma_f32_16x16x32_bf16 v[32:35], v[162:165], v[144:147], 0
	v_mfma_f32_16x16x32_bf16 v[32:35], v[166:169], v[148:151], v[32:35]
	v_mfma_f32_16x16x32_bf16 v[36:39], v[170:173], v[144:147], 0
	v_mfma_f32_16x16x32_bf16 v[36:39], v[174:177], v[148:151], v[36:39]
	v_mfma_f32_16x16x32_bf16 v[48:51], v[162:165], v[152:155], 0
	v_mfma_f32_16x16x32_bf16 v[48:51], v[166:169], v[156:159], v[48:51]
	v_mfma_f32_16x16x32_bf16 v[52:55], v[170:173], v[152:155], 0
	v_mfma_f32_16x16x32_bf16 v[52:55], v[174:177], v[156:159], v[52:55]
	s_setprio 0
	s_barrier
	ds_read_b128 v[224:227], v208 offset:4096
	s_add_u32 m0, s41, 0x0
	ds_read_b128 v[228:231], v209 offset:4096
	global_load_lds_dwordx4 v212, s[24:25]
	s_add_u32 m0, s41, 0x400
	ds_read_b128 v[232:235], v208 offset:6144
	ds_read_b128 v[236:239], v209 offset:6144
	global_load_lds_dwordx4 v213, s[24:25]
	s_barrier
	s_waitcnt lgkmcnt(0)
	s_setprio 1
	v_mfma_f32_16x16x32_bf16 v[8:11], v[224:227], v[128:131], 0
	v_mfma_f32_16x16x32_bf16 v[8:11], v[228:231], v[132:135], v[8:11]
	v_mfma_f32_16x16x32_bf16 v[12:15], v[232:235], v[128:131], 0
	v_mfma_f32_16x16x32_bf16 v[12:15], v[236:239], v[132:135], v[12:15]
	v_mfma_f32_16x16x32_bf16 v[24:27], v[224:227], v[136:139], 0
	v_mfma_f32_16x16x32_bf16 v[24:27], v[228:231], v[140:143], v[24:27]
	v_mfma_f32_16x16x32_bf16 v[28:31], v[232:235], v[136:139], 0
	v_mfma_f32_16x16x32_bf16 v[28:31], v[236:239], v[140:143], v[28:31]
	v_mfma_f32_16x16x32_bf16 v[40:43], v[224:227], v[144:147], 0
	v_mfma_f32_16x16x32_bf16 v[40:43], v[228:231], v[148:151], v[40:43]
	v_mfma_f32_16x16x32_bf16 v[44:47], v[232:235], v[144:147], 0
	v_mfma_f32_16x16x32_bf16 v[44:47], v[236:239], v[148:151], v[44:47]
	v_mfma_f32_16x16x32_bf16 v[56:59], v[224:227], v[152:155], 0
	v_mfma_f32_16x16x32_bf16 v[56:59], v[228:231], v[156:159], v[56:59]
	v_mfma_f32_16x16x32_bf16 v[60:63], v[232:235], v[152:155], 0
	v_mfma_f32_16x16x32_bf16 v[60:63], v[236:239], v[156:159], v[60:63]
	s_setprio 0
	s_barrier
	ds_read_b128 v[128:131], v204 offset:8192
	ds_read_b128 v[132:135], v205 offset:8192
	s_add_u32 m0, s14, 0x0
	ds_read_b128 v[136:139], v204 offset:10240
	ds_read_b128 v[140:143], v205 offset:10240
	global_load_lds_dwordx4 v220, s[22:23]
	s_add_u32 m0, s14, 0x400
	ds_read_b128 v[144:147], v204 offset:12288
	ds_read_b128 v[148:151], v205 offset:12288
	ds_read_b128 v[152:155], v204 offset:14336
	ds_read_b128 v[156:159], v205 offset:14336
	global_load_lds_dwordx4 v221, s[22:23]
	s_barrier
	s_waitcnt lgkmcnt(0)
	s_setprio 1
	v_mfma_f32_16x16x32_bf16 v[64:67], v[162:165], v[128:131], 0
	v_mfma_f32_16x16x32_bf16 v[64:67], v[166:169], v[132:135], v[64:67]
	v_mfma_f32_16x16x32_bf16 v[68:71], v[170:173], v[128:131], 0
	v_mfma_f32_16x16x32_bf16 v[68:71], v[174:177], v[132:135], v[68:71]
	v_mfma_f32_16x16x32_bf16 v[80:83], v[162:165], v[136:139], 0
	v_mfma_f32_16x16x32_bf16 v[80:83], v[166:169], v[140:143], v[80:83]
	v_mfma_f32_16x16x32_bf16 v[84:87], v[170:173], v[136:139], 0
	v_mfma_f32_16x16x32_bf16 v[84:87], v[174:177], v[140:143], v[84:87]
	v_mfma_f32_16x16x32_bf16 v[96:99], v[162:165], v[144:147], 0
	v_mfma_f32_16x16x32_bf16 v[96:99], v[166:169], v[148:151], v[96:99]
	v_mfma_f32_16x16x32_bf16 v[100:103], v[170:173], v[144:147], 0
	v_mfma_f32_16x16x32_bf16 v[100:103], v[174:177], v[148:151], v[100:103]
	v_mfma_f32_16x16x32_bf16 v[112:115], v[162:165], v[152:155], 0
	v_mfma_f32_16x16x32_bf16 v[112:115], v[166:169], v[156:159], v[112:115]
	v_mfma_f32_16x16x32_bf16 v[116:119], v[170:173], v[152:155], 0
	v_mfma_f32_16x16x32_bf16 v[116:119], v[174:177], v[156:159], v[116:119]
	s_setprio 0
	s_barrier
	s_add_u32 m0, s41, 0x1000
	s_nop 0
	global_load_lds_dwordx4 v214, s[24:25]
	s_add_u32 m0, s41, 0x1400
	s_nop 0
	global_load_lds_dwordx4 v215, s[24:25]
	s_waitcnt vmcnt(6)
	s_barrier
	s_setprio 1
	v_mfma_f32_16x16x32_bf16 v[72:75], v[224:227], v[128:131], 0
	v_mfma_f32_16x16x32_bf16 v[72:75], v[228:231], v[132:135], v[72:75]
	v_mfma_f32_16x16x32_bf16 v[76:79], v[232:235], v[128:131], 0
	v_mfma_f32_16x16x32_bf16 v[76:79], v[236:239], v[132:135], v[76:79]
	v_mfma_f32_16x16x32_bf16 v[88:91], v[224:227], v[136:139], 0
	v_mfma_f32_16x16x32_bf16 v[88:91], v[228:231], v[140:143], v[88:91]
	v_mfma_f32_16x16x32_bf16 v[92:95], v[232:235], v[136:139], 0
	v_mfma_f32_16x16x32_bf16 v[92:95], v[236:239], v[140:143], v[92:95]
	v_mfma_f32_16x16x32_bf16 v[104:107], v[224:227], v[144:147], 0
	v_mfma_f32_16x16x32_bf16 v[104:107], v[228:231], v[148:151], v[104:107]
	v_mfma_f32_16x16x32_bf16 v[108:111], v[232:235], v[144:147], 0
	v_mfma_f32_16x16x32_bf16 v[108:111], v[236:239], v[148:151], v[108:111]
	v_mfma_f32_16x16x32_bf16 v[120:123], v[224:227], v[152:155], 0
	v_mfma_f32_16x16x32_bf16 v[120:123], v[228:231], v[156:159], v[120:123]
	v_mfma_f32_16x16x32_bf16 v[124:127], v[232:235], v[152:155], 0
	v_mfma_f32_16x16x32_bf16 v[124:127], v[236:239], v[156:159], v[124:127]
	s_setprio 0
	s_barrier
	ds_read_b128 v[162:165], v210
	ds_read_b128 v[166:169], v211
	ds_read_b128 v[170:173], v210 offset:2048
	ds_read_b128 v[174:177], v211 offset:2048
	s_add_u32 m0, s14, 0x2000
	ds_read_b128 v[128:131], v206
	ds_read_b128 v[132:135], v207
	ds_read_b128 v[136:139], v206 offset:2048
	ds_read_b128 v[140:143], v207 offset:2048
	global_load_lds_dwordx4 v222, s[22:23]
	s_add_u32 m0, s14, 0x2400
	ds_read_b128 v[144:147], v206 offset:4096
	ds_read_b128 v[148:151], v207 offset:4096
	ds_read_b128 v[152:155], v206 offset:6144
	ds_read_b128 v[156:159], v207 offset:6144
	global_load_lds_dwordx4 v223, s[22:23]
	s_add_u32 s22, s22, 0x80
	s_addc_u32 s23, s23, 0
	s_add_u32 s24, s24, 0x80
	s_addc_u32 s25, s25, 0
	s_add_u32 s26, s26, 1
	s_cmp_eq_u32 s26, s50
	s_cbranch_scc0 .Lgm_cadv_done3
	s_mov_b32 s26, 0
	s_add_u32 s27, s27, s30
	s_cmp_lt_u32 s27, s29
	s_cbranch_scc1 .Lgm_cadv_new3
	s_lshl_b32 s53, s50, 7
	s_sub_u32 s22, s22, s53
	s_subb_u32 s23, s23, 0
	s_sub_u32 s24, s24, s53
	s_subb_u32 s25, s25, 0
	s_branch .Lgm_cadv_done3

; #define RAWBAR() { asm volatile("s_waitcnt vmcnt(0) lgkmcnt(0)" ::: "memory"); __builtin_amdgcn_s_barrier(); }
;     ...
;   if (V != 1) GLDS(0, 0);
;   RAWBAR();
;   for (int kt = 0; kt < nk; kt += 2) {
;     if (V != 1) GLDS(kt + 1, 1);
;     if (V != 2) COMPUTE(0);
;     RAWBAR();
;     if (V != 1) if (kt + 2 < nk) GLDS(kt + 2, 0);
;     if (V != 2) COMPUTE(1);
;     RAWBAR();
.Lgm_cadv_done3:
	s_waitcnt lgkmcnt(8)
	s_barrier
	s_waitcnt lgkmcnt(0)
	s_setprio 1
	v_mfma_f32_16x16x32_bf16 v[0:3], v[162:165], v[128:131], v[0:3]
	v_mfma_f32_16x16x32_bf16 v[0:3], v[166:169], v[132:135], v[0:3]
	v_mfma_f32_16x16x32_bf16 v[4:7], v[170:173], v[128:131], v[4:7]
	v_mfma_f32_16x16x32_bf16 v[4:7], v[174:177], v[132:135], v[4:7]
	v_mfma_f32_16x16x32_bf16 v[16:19], v[162:165], v[136:139], v[16:19]
	v_mfma_f32_16x16x32_bf16 v[16:19], v[166:169], v[140:143], v[16:19]
	v_mfma_f32_16x16x32_bf16 v[20:23], v[170:173], v[136:139], v[20:23]
	v_mfma_f32_16x16x32_bf16 v[20:23], v[174:177], v[140:143], v[20:23]
	v_mfma_f32_16x16x32_bf16 v[32:35], v[162:165], v[144:147], v[32:35]
	v_mfma_f32_16x16x32_bf16 v[32:35], v[166:169], v[148:151], v[32:35]
	v_mfma_f32_16x16x32_bf16 v[36:39], v[170:173], v[144:147], v[36:39]
	v_mfma_f32_16x16x32_bf16 v[36:39], v[174:177], v[148:151], v[36:39]
	v_mfma_f32_16x16x32_bf16 v[48:51], v[162:165], v[152:155], v[48:51]
	v_mfma_f32_16x16x32_bf16 v[48:51], v[166:169], v[156:159], v[48:51]
	v_mfma_f32_16x16x32_bf16 v[52:55], v[170:173], v[152:155], v[52:55]
	v_mfma_f32_16x16x32_bf16 v[52:55], v[174:177], v[156:159], v[52:55]
	s_setprio 0
	s_barrier
	ds_read_b128 v[224:227], v210 offset:4096
	s_add_u32 m0, s41, 0x10000
	ds_read_b128 v[228:231], v211 offset:4096
	global_load_lds_dwordx4 v212, s[24:25]
	s_add_u32 m0, s41, 0x10400
	ds_read_b128 v[232:235], v210 offset:6144
	ds_read_b128 v[236:239], v211 offset:6144
	global_load_lds_dwordx4 v213, s[24:25]
	s_barrier
	s_waitcnt lgkmcnt(0)
	s_setprio 1
	v_mfma_f32_16x16x32_bf16 v[8:11], v[224:227], v[128:131], v[8:11]
	v_mfma_f32_16x16x32_bf16 v[8:11], v[228:231], v[132:135], v[8:11]
	v_mfma_f32_16x16x32_bf16 v[12:15], v[232:235], v[128:131], v[12:15]
	v_mfma_f32_16x16x32_bf16 v[12:15], v[236:239], v[132:135], v[12:15]
	v_mfma_f32_16x16x32_bf16 v[24:27], v[224:227], v[136:139], v[24:27]
	v_mfma_f32_16x16x32_bf16 v[24:27], v[228:231], v[140:143], v[24:27]
	v_mfma_f32_16x16x32_bf16 v[28:31], v[232:235], v[136:139], v[28:31]
	v_mfma_f32_16x16x32_bf16 v[28:31], v[236:239], v[140:143], v[28:31]
	v_mfma_f32_16x16x32_bf16 v[40:43], v[224:227], v[144:147], v[40:43]
	v_mfma_f32_16x16x32_bf16 v[40:43], v[228:231], v[148:151], v[40:43]
	v_mfma_f32_16x16x32_bf16 v[44:47], v[232:235], v[144:147], v[44:47]
	v_mfma_f32_16x16x32_bf16 v[44:47], v[236:239], v[148:151], v[44:47]
	v_mfma_f32_16x16x32_bf16 v[56:59], v[224:227], v[152:155], v[56:59]
	v_mfma_f32_16x16x32_bf16 v[56:59], v[228:231], v[156:159], v[56:59]
	v_mfma_f32_16x16x32_bf16 v[60:63], v[232:235], v[152:155], v[60:63]
	v_mfma_f32_16x16x32_bf16 v[60:63], v[236:239], v[156:159], v[60:63]
	s_setprio 0
	s_barrier
	ds_read_b128 v[128:131], v206 offset:8192
	ds_read_b128 v[132:135], v207 offset:8192
	s_add_u32 m0, s14, 0x10000
	ds_read_b128 v[136:139], v206 offset:10240
	ds_read_b128 v[140:143], v207 offset:10240
	global_load_lds_dwordx4 v220, s[22:23]
	s_add_u32 m0, s14, 0x10400
	ds_read_b128 v[144:147], v206 offset:12288
	ds_read_b128 v[148:151], v207 offset:12288
	ds_read_b128 v[152:155], v206 offset:14336
	ds_read_b128 v[156:159], v207 offset:14336
	global_load_lds_dwordx4 v221, s[22:23]
	s_barrier
	s_waitcnt lgkmcnt(0)
	s_setprio 1
	v_mfma_f32_16x16x32_bf16 v[64:67], v[162:165], v[128:131], v[64:67]
	v_mfma_f32_16x16x32_bf16 v[64:67], v[166:169], v[132:135], v[64:67]
	v_mfma_f32_16x16x32_bf16 v[68:71], v[170:173], v[128:131], v[68:71]
	v_mfma_f32_16x16x32_bf16 v[68:71], v[174:177], v[132:135], v[68:71]
	v_mfma_f32_16x16x32_bf16 v[80:83], v[162:165], v[136:139], v[80:83]
	v_mfma_f32_16x16x32_bf16 v[80:83], v[166:169], v[140:143], v[80:83]
	v_mfma_f32_16x16x32_bf16 v[84:87], v[170:173], v[136:139], v[84:87]
	v_mfma_f32_16x16x32_bf16 v[84:87], v[174:177], v[140:143], v[84:87]
	v_mfma_f32_16x16x32_bf16 v[96:99], v[162:165], v[144:147], v[96:99]
	v_mfma_f32_16x16x32_bf16 v[96:99], v[166:169], v[148:151], v[96:99]
	v_mfma_f32_16x16x32_bf16 v[100:103], v[170:173], v[144:147], v[100:103]
	v_mfma_f32_16x16x32_bf16 v[100:103], v[174:177], v[148:151], v[100:103]
	v_mfma_f32_16x16x32_bf16 v[112:115], v[162:165], v[152:155], v[112:115]
	v_mfma_f32_16x16x32_bf16 v[112:115], v[166:169], v[156:159], v[112:115]
	v_mfma_f32_16x16x32_bf16 v[116:119], v[170:173], v[152:155], v[116:119]
	v_mfma_f32_16x16x32_bf16 v[116:119], v[174:177], v[156:159], v[116:119]
	s_setprio 0
	s_barrier
	s_add_u32 m0, s41, 0x11000
	s_nop 0
	global_load_lds_dwordx4 v214, s[24:25]
	s_add_u32 m0, s41, 0x11400
	s_nop 0
	global_load_lds_dwordx4 v215, s[24:25]
	s_waitcnt vmcnt(6)
	s_barrier
	s_setprio 1
	v_mfma_f32_16x16x32_bf16 v[72:75], v[224:227], v[128:131], v[72:75]
	v_mfma_f32_16x16x32_bf16 v[72:75], v[228:231], v[132:135], v[72:75]
	v_mfma_f32_16x16x32_bf16 v[76:79], v[232:235], v[128:131], v[76:79]
	v_mfma_f32_16x16x32_bf16 v[76:79], v[236:239], v[132:135], v[76:79]
	v_mfma_f32_16x16x32_bf16 v[88:91], v[224:227], v[136:139], v[88:91]
	v_mfma_f32_16x16x32_bf16 v[88:91], v[228:231], v[140:143], v[88:91]
	v_mfma_f32_16x16x32_bf16 v[92:95], v[232:235], v[136:139], v[92:95]
	v_mfma_f32_16x16x32_bf16 v[92:95], v[236:239], v[140:143], v[92:95]
	v_mfma_f32_16x16x32_bf16 v[104:107], v[224:227], v[144:147], v[104:107]
	v_mfma_f32_16x16x32_bf16 v[104:107], v[228:231], v[148:151], v[104:107]
	v_mfma_f32_16x16x32_bf16 v[108:111], v[232:235], v[144:147], v[108:111]
	v_mfma_f32_16x16x32_bf16 v[108:111], v[236:239], v[148:151], v[108:111]
	v_mfma_f32_16x16x32_bf16 v[120:123], v[224:227], v[152:155], v[120:123]
	v_mfma_f32_16x16x32_bf16 v[120:123], v[228:231], v[156:159], v[120:123]
	v_mfma_f32_16x16x32_bf16 v[124:127], v[232:235], v[152:155], v[124:127]
	v_mfma_f32_16x16x32_bf16 v[124:127], v[236:239], v[156:159], v[124:127]
	s_setprio 0
	s_barrier
	s_mov_b32 s52, s51
	s_cmp_eq_u32 s52, 0
	s_cbranch_scc1 .Lgm_pairs_done

; #define RAWBAR() { asm volatile("s_waitcnt vmcnt(0) lgkmcnt(0)" ::: "memory"); __builtin_amdgcn_s_barrier(); }
;     ...
;   for (int kt = 0; kt < nk; kt += 2) {
;     if (V != 1) GLDS(kt + 1, 1);
;     if (V != 2) COMPUTE(0);
;     RAWBAR();
;     if (V != 1) if (kt + 2 < nk) GLDS(kt + 2, 0);
;     if (V != 2) COMPUTE(1);
;     RAWBAR();
.Lgm_cadv_done4:
	s_waitcnt lgkmcnt(8)
	s_barrier
	s_waitcnt lgkmcnt(0)
	s_setprio 1
	v_mfma_f32_16x16x32_bf16 v[0:3], v[162:165], v[128:131], v[0:3]
	v_mfma_f32_16x16x32_bf16 v[0:3], v[166:169], v[132:135], v[0:3]
	v_mfma_f32_16x16x32_bf16 v[4:7], v[170:173], v[128:131], v[4:7]
	v_mfma_f32_16x16x32_bf16 v[4:7], v[174:177], v[132:135], v[4:7]
	v_mfma_f32_16x16x32_bf16 v[16:19], v[162:165], v[136:139], v[16:19]
	v_mfma_f32_16x16x32_bf16 v[16:19], v[166:169], v[140:143], v[16:19]
	v_mfma_f32_16x16x32_bf16 v[20:23], v[170:173], v[136:139], v[20:23]
	v_mfma_f32_16x16x32_bf16 v[20:23], v[174:177], v[140:143], v[20:23]
	v_mfma_f32_16x16x32_bf16 v[32:35], v[162:165], v[144:147], v[32:35]
	v_mfma_f32_16x16x32_bf16 v[32:35], v[166:169], v[148:151], v[32:35]
	v_mfma_f32_16x16x32_bf16 v[36:39], v[170:173], v[144:147], v[36:39]
	v_mfma_f32_16x16x32_bf16 v[36:39], v[174:177], v[148:151], v[36:39]
	v_mfma_f32_16x16x32_bf16 v[48:51], v[162:165], v[152:155], v[48:51]
	v_mfma_f32_16x16x32_bf16 v[48:51], v[166:169], v[156:159], v[48:51]
	v_mfma_f32_16x16x32_bf16 v[52:55], v[170:173], v[152:155], v[52:55]
	v_mfma_f32_16x16x32_bf16 v[52:55], v[174:177], v[156:159], v[52:55]
	s_setprio 0
	s_barrier
	ds_read_b128 v[224:227], v208 offset:4096
	s_add_u32 m0, s41, 0x0
	ds_read_b128 v[228:231], v209 offset:4096
	global_load_lds_dwordx4 v212, s[24:25]
	s_add_u32 m0, s41, 0x400
	ds_read_b128 v[232:235], v208 offset:6144
	ds_read_b128 v[236:239], v209 offset:6144
	global_load_lds_dwordx4 v213, s[24:25]
	s_barrier
	s_waitcnt lgkmcnt(0)
	s_setprio 1
	v_mfma_f32_16x16x32_bf16 v[8:11], v[224:227], v[128:131], v[8:11]
	v_mfma_f32_16x16x32_bf16 v[8:11], v[228:231], v[132:135], v[8:11]
	v_mfma_f32_16x16x32_bf16 v[12:15], v[232:235], v[128:131], v[12:15]
	v_mfma_f32_16x16x32_bf16 v[12:15], v[236:239], v[132:135], v[12:15]
	v_mfma_f32_16x16x32_bf16 v[24:27], v[224:227], v[136:139], v[24:27]
	v_mfma_f32_16x16x32_bf16 v[24:27], v[228:231], v[140:143], v[24:27]
	v_mfma_f32_16x16x32_bf16 v[28:31], v[232:235], v[136:139], v[28:31]
	v_mfma_f32_16x16x32_bf16 v[28:31], v[236:239], v[140:143], v[28:31]
	v_mfma_f32_16x16x32_bf16 v[40:43], v[224:227], v[144:147], v[40:43]
	v_mfma_f32_16x16x32_bf16 v[40:43], v[228:231], v[148:151], v[40:43]
	v_mfma_f32_16x16x32_bf16 v[44:47], v[232:235], v[144:147], v[44:47]
	v_mfma_f32_16x16x32_bf16 v[44:47], v[236:239], v[148:151], v[44:47]
	v_mfma_f32_16x16x32_bf16 v[56:59], v[224:227], v[152:155], v[56:59]
	v_mfma_f32_16x16x32_bf16 v[56:59], v[228:231], v[156:159], v[56:59]
	v_mfma_f32_16x16x32_bf16 v[60:63], v[232:235], v[152:155], v[60:63]
	v_mfma_f32_16x16x32_bf16 v[60:63], v[236:239], v[156:159], v[60:63]
	s_setprio 0
	s_barrier
	ds_read_b128 v[128:131], v204 offset:8192
	ds_read_b128 v[132:135], v205 offset:8192
	s_add_u32 m0, s14, 0x0
	ds_read_b128 v[136:139], v204 offset:10240
	ds_read_b128 v[140:143], v205 offset:10240
	global_load_lds_dwordx4 v220, s[22:23]
	s_add_u32 m0, s14, 0x400
	ds_read_b128 v[144:147], v204 offset:12288
	ds_read_b128 v[148:151], v205 offset:12288
	ds_read_b128 v[152:155], v204 offset:14336
	ds_read_b128 v[156:159], v205 offset:14336
	global_load_lds_dwordx4 v221, s[22:23]
	s_barrier
	s_waitcnt lgkmcnt(0)
	s_setprio 1
	v_mfma_f32_16x16x32_bf16 v[64:67], v[162:165], v[128:131], v[64:67]
	v_mfma_f32_16x16x32_bf16 v[64:67], v[166:169], v[132:135], v[64:67]
	v_mfma_f32_16x16x32_bf16 v[68:71], v[170:173], v[128:131], v[68:71]
	v_mfma_f32_16x16x32_bf16 v[68:71], v[174:177], v[132:135], v[68:71]
	v_mfma_f32_16x16x32_bf16 v[80:83], v[162:165], v[136:139], v[80:83]
	v_mfma_f32_16x16x32_bf16 v[80:83], v[166:169], v[140:143], v[80:83]
	v_mfma_f32_16x16x32_bf16 v[84:87], v[170:173], v[136:139], v[84:87]
	v_mfma_f32_16x16x32_bf16 v[84:87], v[174:177], v[140:143], v[84:87]
	v_mfma_f32_16x16x32_bf16 v[96:99], v[162:165], v[144:147], v[96:99]
	v_mfma_f32_16x16x32_bf16 v[96:99], v[166:169], v[148:151], v[96:99]
	v_mfma_f32_16x16x32_bf16 v[100:103], v[170:173], v[144:147], v[100:103]
	v_mfma_f32_16x16x32_bf16 v[100:103], v[174:177], v[148:151], v[100:103]
	v_mfma_f32_16x16x32_bf16 v[112:115], v[162:165], v[152:155], v[112:115]
	v_mfma_f32_16x16x32_bf16 v[112:115], v[166:169], v[156:159], v[112:115]
	v_mfma_f32_16x16x32_bf16 v[116:119], v[170:173], v[152:155], v[116:119]
	v_mfma_f32_16x16x32_bf16 v[116:119], v[174:177], v[156:159], v[116:119]
	s_setprio 0
	s_barrier
	s_add_u32 m0, s41, 0x1000
	s_nop 0
	global_load_lds_dwordx4 v214, s[24:25]
	s_add_u32 m0, s41, 0x1400
	s_nop 0
	global_load_lds_dwordx4 v215, s[24:25]
	s_waitcnt vmcnt(6)
	s_barrier
	s_setprio 1
	v_mfma_f32_16x16x32_bf16 v[72:75], v[224:227], v[128:131], v[72:75]
	v_mfma_f32_16x16x32_bf16 v[72:75], v[228:231], v[132:135], v[72:75]
	v_mfma_f32_16x16x32_bf16 v[76:79], v[232:235], v[128:131], v[76:79]
	v_mfma_f32_16x16x32_bf16 v[76:79], v[236:239], v[132:135], v[76:79]
	v_mfma_f32_16x16x32_bf16 v[88:91], v[224:227], v[136:139], v[88:91]
	v_mfma_f32_16x16x32_bf16 v[88:91], v[228:231], v[140:143], v[88:91]
	v_mfma_f32_16x16x32_bf16 v[92:95], v[232:235], v[136:139], v[92:95]
	v_mfma_f32_16x16x32_bf16 v[92:95], v[236:239], v[140:143], v[92:95]
	v_mfma_f32_16x16x32_bf16 v[104:107], v[224:227], v[144:147], v[104:107]
	v_mfma_f32_16x16x32_bf16 v[104:107], v[228:231], v[148:151], v[104:107]
	v_mfma_f32_16x16x32_bf16 v[108:111], v[232:235], v[144:147], v[108:111]
	v_mfma_f32_16x16x32_bf16 v[108:111], v[236:239], v[148:151], v[108:111]
	v_mfma_f32_16x16x32_bf16 v[120:123], v[224:227], v[152:155], v[120:123]
	v_mfma_f32_16x16x32_bf16 v[120:123], v[228:231], v[156:159], v[120:123]
	v_mfma_f32_16x16x32_bf16 v[124:127], v[232:235], v[152:155], v[124:127]
	v_mfma_f32_16x16x32_bf16 v[124:127], v[236:239], v[156:159], v[124:127]
	s_setprio 0
	s_barrier
	ds_read_b128 v[162:165], v210
	ds_read_b128 v[166:169], v211
	ds_read_b128 v[170:173], v210 offset:2048
	ds_read_b128 v[174:177], v211 offset:2048
	s_add_u32 m0, s14, 0x2000
	ds_read_b128 v[128:131], v206
	ds_read_b128 v[132:135], v207
	ds_read_b128 v[136:139], v206 offset:2048
	ds_read_b128 v[140:143], v207 offset:2048
	global_load_lds_dwordx4 v222, s[22:23]
	s_add_u32 m0, s14, 0x2400
	ds_read_b128 v[144:147], v206 offset:4096
	ds_read_b128 v[148:151], v207 offset:4096
	ds_read_b128 v[152:155], v206 offset:6144
	ds_read_b128 v[156:159], v207 offset:6144
	global_load_lds_dwordx4 v223, s[22:23]
	s_add_u32 s22, s22, 0x80
	s_addc_u32 s23, s23, 0
	s_add_u32 s24, s24, 0x80
	s_addc_u32 s25, s25, 0
	s_add_u32 s26, s26, 1
	s_cmp_eq_u32 s26, s50
	s_cbranch_scc0 .Lgm_cadv_done5
	s_mov_b32 s26, 0
	s_add_u32 s27, s27, s30
	s_cmp_lt_u32 s27, s29
	s_cbranch_scc1 .Lgm_cadv_new5
	s_lshl_b32 s53, s50, 7
	s_sub_u32 s22, s22, s53
	s_subb_u32 s23, s23, 0
	s_sub_u32 s24, s24, s53
	s_subb_u32 s25, s25, 0
	s_branch .Lgm_cadv_done5

; #define RAWBAR() { asm volatile("s_waitcnt vmcnt(0) lgkmcnt(0)" ::: "memory"); __builtin_amdgcn_s_barrier(); }
;     ...
;   for (int kt = 0; kt < nk; kt += 2) {
;     if (V != 1) GLDS(kt + 1, 1);
;     if (V != 2) COMPUTE(0);
;     RAWBAR();
;     if (V != 1) if (kt + 2 < nk) GLDS(kt + 2, 0);
;     if (V != 2) COMPUTE(1);
;     RAWBAR();
.Lgm_cadv_done5:
	s_waitcnt lgkmcnt(8)
	s_barrier
	s_waitcnt lgkmcnt(0)
	s_setprio 1
	v_mfma_f32_16x16x32_bf16 v[0:3], v[162:165], v[128:131], v[0:3]
	v_mfma_f32_16x16x32_bf16 v[0:3], v[166:169], v[132:135], v[0:3]
	v_mfma_f32_16x16x32_bf16 v[4:7], v[170:173], v[128:131], v[4:7]
	v_mfma_f32_16x16x32_bf16 v[4:7], v[174:177], v[132:135], v[4:7]
	v_mfma_f32_16x16x32_bf16 v[16:19], v[162:165], v[136:139], v[16:19]
	v_mfma_f32_16x16x32_bf16 v[16:19], v[166:169], v[140:143], v[16:19]
	v_mfma_f32_16x16x32_bf16 v[20:23], v[170:173], v[136:139], v[20:23]
	v_mfma_f32_16x16x32_bf16 v[20:23], v[174:177], v[140:143], v[20:23]
	v_mfma_f32_16x16x32_bf16 v[32:35], v[162:165], v[144:147], v[32:35]
	v_mfma_f32_16x16x32_bf16 v[32:35], v[166:169], v[148:151], v[32:35]
	v_mfma_f32_16x16x32_bf16 v[36:39], v[170:173], v[144:147], v[36:39]
	v_mfma_f32_16x16x32_bf16 v[36:39], v[174:177], v[148:151], v[36:39]
	v_mfma_f32_16x16x32_bf16 v[48:51], v[162:165], v[152:155], v[48:51]
	v_mfma_f32_16x16x32_bf16 v[48:51], v[166:169], v[156:159], v[48:51]
	v_mfma_f32_16x16x32_bf16 v[52:55], v[170:173], v[152:155], v[52:55]
	v_mfma_f32_16x16x32_bf16 v[52:55], v[174:177], v[156:159], v[52:55]
	s_setprio 0
	s_barrier
	ds_read_b128 v[224:227], v210 offset:4096
	s_add_u32 m0, s41, 0x10000
	ds_read_b128 v[228:231], v211 offset:4096
	global_load_lds_dwordx4 v212, s[24:25]
	s_add_u32 m0, s41, 0x10400
	ds_read_b128 v[232:235], v210 offset:6144
	ds_read_b128 v[236:239], v211 offset:6144
	global_load_lds_dwordx4 v213, s[24:25]
	s_barrier
	s_waitcnt lgkmcnt(0)
	s_setprio 1
	v_mfma_f32_16x16x32_bf16 v[8:11], v[224:227], v[128:131], v[8:11]
	v_mfma_f32_16x16x32_bf16 v[8:11], v[228:231], v[132:135], v[8:11]
	v_mfma_f32_16x16x32_bf16 v[12:15], v[232:235], v[128:131], v[12:15]
	v_mfma_f32_16x16x32_bf16 v[12:15], v[236:239], v[132:135], v[12:15]
	v_mfma_f32_16x16x32_bf16 v[24:27], v[224:227], v[136:139], v[24:27]
	v_mfma_f32_16x16x32_bf16 v[24:27], v[228:231], v[140:143], v[24:27]
	v_mfma_f32_16x16x32_bf16 v[28:31], v[232:235], v[136:139], v[28:31]
	v_mfma_f32_16x16x32_bf16 v[28:31], v[236:239], v[140:143], v[28:31]
	v_mfma_f32_16x16x32_bf16 v[40:43], v[224:227], v[144:147], v[40:43]
	v_mfma_f32_16x16x32_bf16 v[40:43], v[228:231], v[148:151], v[40:43]
	v_mfma_f32_16x16x32_bf16 v[44:47], v[232:235], v[144:147], v[44:47]
	v_mfma_f32_16x16x32_bf16 v[44:47], v[236:239], v[148:151], v[44:47]
	v_mfma_f32_16x16x32_bf16 v[56:59], v[224:227], v[152:155], v[56:59]
	v_mfma_f32_16x16x32_bf16 v[56:59], v[228:231], v[156:159], v[56:59]
	v_mfma_f32_16x16x32_bf16 v[60:63], v[232:235], v[152:155], v[60:63]
	v_mfma_f32_16x16x32_bf16 v[60:63], v[236:239], v[156:159], v[60:63]
	s_setprio 0
	s_barrier
	ds_read_b128 v[128:131], v206 offset:8192
	ds_read_b128 v[132:135], v207 offset:8192
	s_add_u32 m0, s14, 0x10000
	ds_read_b128 v[136:139], v206 offset:10240
	ds_read_b128 v[140:143], v207 offset:10240
	global_load_lds_dwordx4 v220, s[22:23]
	s_add_u32 m0, s14, 0x10400
	ds_read_b128 v[144:147], v206 offset:12288
	ds_read_b128 v[148:151], v207 offset:12288
	ds_read_b128 v[152:155], v206 offset:14336
	ds_read_b128 v[156:159], v207 offset:14336
	global_load_lds_dwordx4 v221, s[22:23]
	s_barrier
	s_waitcnt lgkmcnt(0)
	s_setprio 1
	v_mfma_f32_16x16x32_bf16 v[64:67], v[162:165], v[128:131], v[64:67]
	v_mfma_f32_16x16x32_bf16 v[64:67], v[166:169], v[132:135], v[64:67]
	v_mfma_f32_16x16x32_bf16 v[68:71], v[170:173], v[128:131], v[68:71]
	v_mfma_f32_16x16x32_bf16 v[68:71], v[174:177], v[132:135], v[68:71]
	v_mfma_f32_16x16x32_bf16 v[80:83], v[162:165], v[136:139], v[80:83]
	v_mfma_f32_16x16x32_bf16 v[80:83], v[166:169], v[140:143], v[80:83]
	v_mfma_f32_16x16x32_bf16 v[84:87], v[170:173], v[136:139], v[84:87]
	v_mfma_f32_16x16x32_bf16 v[84:87], v[174:177], v[140:143], v[84:87]
	v_mfma_f32_16x16x32_bf16 v[96:99], v[162:165], v[144:147], v[96:99]
	v_mfma_f32_16x16x32_bf16 v[96:99], v[166:169], v[148:151], v[96:99]
	v_mfma_f32_16x16x32_bf16 v[100:103], v[170:173], v[144:147], v[100:103]
	v_mfma_f32_16x16x32_bf16 v[100:103], v[174:177], v[148:151], v[100:103]
	v_mfma_f32_16x16x32_bf16 v[112:115], v[162:165], v[152:155], v[112:115]
	v_mfma_f32_16x16x32_bf16 v[112:115], v[166:169], v[156:159], v[112:115]
	v_mfma_f32_16x16x32_bf16 v[116:119], v[170:173], v[152:155], v[116:119]
	v_mfma_f32_16x16x32_bf16 v[116:119], v[174:177], v[156:159], v[116:119]
	s_setprio 0
	s_barrier
	s_add_u32 m0, s41, 0x11000
	s_nop 0
	global_load_lds_dwordx4 v214, s[24:25]
	s_add_u32 m0, s41, 0x11400
	s_nop 0
	global_load_lds_dwordx4 v215, s[24:25]
	s_waitcnt vmcnt(6)
	s_barrier
	s_setprio 1
	v_mfma_f32_16x16x32_bf16 v[72:75], v[224:227], v[128:131], v[72:75]
	v_mfma_f32_16x16x32_bf16 v[72:75], v[228:231], v[132:135], v[72:75]
	v_mfma_f32_16x16x32_bf16 v[76:79], v[232:235], v[128:131], v[76:79]
	v_mfma_f32_16x16x32_bf16 v[76:79], v[236:239], v[132:135], v[76:79]
	v_mfma_f32_16x16x32_bf16 v[88:91], v[224:227], v[136:139], v[88:91]
	v_mfma_f32_16x16x32_bf16 v[88:91], v[228:231], v[140:143], v[88:91]
	v_mfma_f32_16x16x32_bf16 v[92:95], v[232:235], v[136:139], v[92:95]
	v_mfma_f32_16x16x32_bf16 v[92:95], v[236:239], v[140:143], v[92:95]
	v_mfma_f32_16x16x32_bf16 v[104:107], v[224:227], v[144:147], v[104:107]
	v_mfma_f32_16x16x32_bf16 v[104:107], v[228:231], v[148:151], v[104:107]
	v_mfma_f32_16x16x32_bf16 v[108:111], v[232:235], v[144:147], v[108:111]
	v_mfma_f32_16x16x32_bf16 v[108:111], v[236:239], v[148:151], v[108:111]
	v_mfma_f32_16x16x32_bf16 v[120:123], v[224:227], v[152:155], v[120:123]
	v_mfma_f32_16x16x32_bf16 v[120:123], v[228:231], v[156:159], v[120:123]
	v_mfma_f32_16x16x32_bf16 v[124:127], v[232:235], v[152:155], v[124:127]
	v_mfma_f32_16x16x32_bf16 v[124:127], v[236:239], v[156:159], v[124:127]
	s_setprio 0
	s_barrier
	s_sub_u32 s52, s52, 1
	s_cmp_lg_u32 s52, 0
	s_cbranch_scc1 .Lgm_pair
; DI int crow(int r, int hf) { return (r & 3) + 8 * (r >> 2) + 4 * hf; }
;     ...
; #pragma unroll
;       for (int i = 0; i < 2; ++i)
; #pragma unroll
;         for (int j = 0; j < 2; ++j)
; #pragma unroll
;           for (int r = 0; r < 16; ++r) {
;             const int row = m0_ + wm * 64 + i * 32 + crow(r, hf_), col = n0 + wn * 64 + j * 32 + l32_;
;             float v = acc[i][j][r];
;             if (mode == 1) { v = fmaxf(v, 0.f); v = v * v; }
;             if (V == 0 || v == 123456.789f) C[(size_t)row * ldc + col] = f2bf(v);
.Lgm_pairs_done:
	s_lshr_b32 s53, s28, 5
	s_and_b32 s54, s28, 31
	s_lshr_b32 s55, s53, s34
	s_lshl_b32 s56, s55, s34
	s_sub_u32 s56, s53, s56
	s_lshl_b32 s55, s55, 3
	s_add_u32 s55, s55, s31
	s_lshr_b32 s57, s54, 2
	s_add_u32 s55, s55, s57
	s_lshl_b32 s56, s56, 2
	s_and_b32 s57, s54, 3
	s_add_u32 s56, s56, s57
	s_lshl_b32 s57, s55, 8
	s_add_u32 s57, s57, s58
	s_mul_i32 s57, s57, s36
	s_add_u32 s38, s12, s57
	s_addc_u32 s39, s13, 0
	s_lshl_b32 s57, s56, 9
	s_add_u32 s57, s57, s59
	s_add_u32 s38, s38, s57
	s_addc_u32 s39, s39, 0
	s_cmp_eq_u64 s[4:5], 0
	s_cbranch_scc1 .Lgm_epi_relu
	v_cvt_pk_bf16_f32 v240, v0, v1
	v_cvt_pk_bf16_f32 v241, v2, v3
	ds_write_b64 v178, v[240:241]
	v_cvt_pk_bf16_f32 v242, v4, v5
	v_cvt_pk_bf16_f32 v243, v6, v7
	ds_write_b64 v179, v[242:243]
	v_cvt_pk_bf16_f32 v244, v8, v9
	v_cvt_pk_bf16_f32 v245, v10, v11
	ds_write_b64 v180, v[244:245]
	v_cvt_pk_bf16_f32 v246, v12, v13
	v_cvt_pk_bf16_f32 v247, v14, v15
	ds_write_b64 v181, v[246:247]
	ds_read_b128 v[0:3], v194
	ds_read_b128 v[4:7], v188 offset:1024
	v_cvt_pk_bf16_f32 v240, v16, v17
	v_cvt_pk_bf16_f32 v241, v18, v19
	ds_write_b64 v178, v[240:241]
	v_cvt_pk_bf16_f32 v242, v20, v21
	v_cvt_pk_bf16_f32 v243, v22, v23
	ds_write_b64 v179, v[242:243]
	v_cvt_pk_bf16_f32 v244, v24, v25
	v_cvt_pk_bf16_f32 v245, v26, v27
	ds_write_b64 v180, v[244:245]
	v_cvt_pk_bf16_f32 v246, v28, v29
	v_cvt_pk_bf16_f32 v247, v30, v31
	ds_write_b64 v181, v[246:247]
	ds_read_b128 v[16:19], v194
	ds_read_b128 v[20:23], v188 offset:1024
	s_waitcnt lgkmcnt(6)
	global_store_dwordx4 v195, v[0:3], s[38:39]
	s_add_u32 s38, s38, s40
	s_addc_u32 s39, s39, 0
	global_store_dwordx4 v195, v[4:7], s[38:39]
	s_add_u32 s38, s38, s40
	s_addc_u32 s39, s39, 0
	v_cvt_pk_bf16_f32 v240, v32, v33
	v_cvt_pk_bf16_f32 v241, v34, v35
	ds_write_b64 v178, v[240:241]
	v_cvt_pk_bf16_f32 v242, v36, v37
	v_cvt_pk_bf16_f32 v243, v38, v39
	ds_write_b64 v179, v[242:243]
	v_cvt_pk_bf16_f32 v244, v40, v41
	v_cvt_pk_bf16_f32 v245, v42, v43
	ds_write_b64 v180, v[244:245]
	v_cvt_pk_bf16_f32 v246, v44, v45
	v_cvt_pk_bf16_f32 v247, v46, v47
	ds_write_b64 v181, v[246:247]
	ds_read_b128 v[32:35], v194
	ds_read_b128 v[36:39], v188 offset:1024
	s_waitcnt lgkmcnt(6)
	global_store_dwordx4 v195, v[16:19], s[38:39]
	s_add_u32 s38, s38, s40
	s_addc_u32 s39, s39, 0
	global_store_dwordx4 v195, v[20:23], s[38:39]
	s_add_u32 s38, s38, s40
	s_addc_u32 s39, s39, 0
	v_cvt_pk_bf16_f32 v240, v48, v49
	v_cvt_pk_bf16_f32 v241, v50, v51
	ds_write_b64 v178, v[240:241]
	v_cvt_pk_bf16_f32 v242, v52, v53
	v_cvt_pk_bf16_f32 v243, v54, v55
	ds_write_b64 v179, v[242:243]
	v_cvt_pk_bf16_f32 v244, v56, v57
	v_cvt_pk_bf16_f32 v245, v58, v59
	ds_write_b64 v180, v[244:245]
	v_cvt_pk_bf16_f32 v246, v60, v61
	v_cvt_pk_bf16_f32 v247, v62, v63
	ds_write_b64 v181, v[246:247]
	ds_read_b128 v[48:51], v194
	ds_read_b128 v[52:55], v188 offset:1024
	s_waitcnt lgkmcnt(6)
	global_store_dwordx4 v195, v[32:35], s[38:39]
	s_add_u32 s38, s38, s40
	s_addc_u32 s39, s39, 0
	global_store_dwordx4 v195, v[36:39], s[38:39]
	s_add_u32 s38, s38, s40
	s_addc_u32 s39, s39, 0
	v_cvt_pk_bf16_f32 v240, v64, v65
	v_cvt_pk_bf16_f32 v241, v66, v67
	ds_write_b64 v178, v[240:241]
	v_cvt_pk_bf16_f32 v242, v68, v69
	v_cvt_pk_bf16_f32 v243, v70, v71
	ds_write_b64 v179, v[242:243]
	v_cvt_pk_bf16_f32 v244, v72, v73
	v_cvt_pk_bf16_f32 v245, v74, v75
	ds_write_b64 v180, v[244:245]
	v_cvt_pk_bf16_f32 v246, v76, v77
	v_cvt_pk_bf16_f32 v247, v78, v79
	ds_write_b64 v181, v[246:247]
	ds_read_b128 v[64:67], v194
	ds_read_b128 v[68:71], v188 offset:1024
	s_waitcnt lgkmcnt(6)
	global_store_dwordx4 v195, v[48:51], s[38:39]
	s_add_u32 s38, s38, s40
	s_addc_u32 s39, s39, 0
	global_store_dwordx4 v195, v[52:55], s[38:39]
	s_add_u32 s38, s38, s40
	s_addc_u32 s39, s39, 0
	v_cvt_pk_bf16_f32 v240, v80, v81
	v_cvt_pk_bf16_f32 v241, v82, v83
	ds_write_b64 v178, v[240:241]
	v_cvt_pk_bf16_f32 v242, v84, v85
	v_cvt_pk_bf16_f32 v243, v86, v87
	ds_write_b64 v179, v[242:243]
	v_cvt_pk_bf16_f32 v244, v88, v89
	v_cvt_pk_bf16_f32 v245, v90, v91
	ds_write_b64 v180, v[244:245]
	v_cvt_pk_bf16_f32 v246, v92, v93
	v_cvt_pk_bf16_f32 v247, v94, v95
	ds_write_b64 v181, v[246:247]
	ds_read_b128 v[80:83], v194
	ds_read_b128 v[84:87], v188 offset:1024
	s_waitcnt lgkmcnt(6)
	global_store_dwordx4 v195, v[64:67], s[38:39]
	s_add_u32 s38, s38, s40
	s_addc_u32 s39, s39, 0
	global_store_dwordx4 v195, v[68:71], s[38:39]
	s_add_u32 s38, s38, s40
	s_addc_u32 s39, s39, 0
	v_cvt_pk_bf16_f32 v240, v96, v97
	v_cvt_pk_bf16_f32 v241, v98, v99
	ds_write_b64 v178, v[240:241]
	v_cvt_pk_bf16_f32 v242, v100, v101
	v_cvt_pk_bf16_f32 v243, v102, v103
	ds_write_b64 v179, v[242:243]
	v_cvt_pk_bf16_f32 v244, v104, v105
	v_cvt_pk_bf16_f32 v245, v106, v107
	ds_write_b64 v180, v[244:245]
	v_cvt_pk_bf16_f32 v246, v108, v109
	v_cvt_pk_bf16_f32 v247, v110, v111
	ds_write_b64 v181, v[246:247]
	ds_read_b128 v[96:99], v194
	ds_read_b128 v[100:103], v188 offset:1024
	s_waitcnt lgkmcnt(6)
	global_store_dwordx4 v195, v[80:83], s[38:39]
	s_add_u32 s38, s38, s40
	s_addc_u32 s39, s39, 0
	global_store_dwordx4 v195, v[84:87], s[38:39]
	s_add_u32 s38, s38, s40
	s_addc_u32 s39, s39, 0
	v_cvt_pk_bf16_f32 v240, v112, v113
	v_cvt_pk_bf16_f32 v241, v114, v115
	ds_write_b64 v178, v[240:241]
	v_cvt_pk_bf16_f32 v242, v116, v117
	v_cvt_pk_bf16_f32 v243, v118, v119
	ds_write_b64 v179, v[242:243]
	v_cvt_pk_bf16_f32 v244, v120, v121
	v_cvt_pk_bf16_f32 v245, v122, v123
	ds_write_b64 v180, v[244:245]
	v_cvt_pk_bf16_f32 v246, v124, v125
	v_cvt_pk_bf16_f32 v247, v126, v127
	ds_write_b64 v181, v[246:247]
	ds_read_b128 v[112:115], v194
	ds_read_b128 v[116:119], v188 offset:1024
	s_waitcnt lgkmcnt(6)
	global_store_dwordx4 v195, v[96:99], s[38:39]
	s_add_u32 s38, s38, s40
	s_addc_u32 s39, s39, 0
	global_store_dwordx4 v195, v[100:103], s[38:39]
	s_add_u32 s38, s38, s40
	s_addc_u32 s39, s39, 0
	s_waitcnt lgkmcnt(0)
	global_store_dwordx4 v195, v[112:115], s[38:39]
	s_add_u32 s38, s38, s40
	s_addc_u32 s39, s39, 0
	global_store_dwordx4 v195, v[116:119], s[38:39]
	s_branch .Lgm_epi_done
; DI int crow(int r, int hf) { return (r & 3) + 8 * (r >> 2) + 4 * hf; }
;     ...
;           for (int r = 0; r < 16; ++r) {
;             const int row = m0_ + wm * 64 + i * 32 + crow(r, hf_), col = n0 + wn * 64 + j * 32 + l32_;
;             float v = acc[i][j][r];
;             if (mode == 1) { v = fmaxf(v, 0.f); v = v * v; }
;             if (V == 0 || v == 123456.789f) C[(size_t)row * ldc + col] = f2bf(v);
.Lgm_epi_relu:
	v_max_f32_e32 v0, 0, v0
	v_max_f32_e32 v1, 0, v1
	v_max_f32_e32 v2, 0, v2
	v_max_f32_e32 v3, 0, v3
	v_mul_f32_e32 v0, v0, v0
	v_mul_f32_e32 v1, v1, v1
	v_mul_f32_e32 v2, v2, v2
	v_mul_f32_e32 v3, v3, v3
	v_cvt_pk_bf16_f32 v240, v0, v1
	v_cvt_pk_bf16_f32 v241, v2, v3
	ds_write_b64 v178, v[240:241]
	v_max_f32_e32 v4, 0, v4
	v_max_f32_e32 v5, 0, v5
	v_max_f32_e32 v6, 0, v6
	v_max_f32_e32 v7, 0, v7
	v_mul_f32_e32 v4, v4, v4
	v_mul_f32_e32 v5, v5, v5
	v_mul_f32_e32 v6, v6, v6
	v_mul_f32_e32 v7, v7, v7
	v_cvt_pk_bf16_f32 v242, v4, v5
	v_cvt_pk_bf16_f32 v243, v6, v7
	ds_write_b64 v179, v[242:243]
	v_max_f32_e32 v8, 0, v8
	v_max_f32_e32 v9, 0, v9
	v_max_f32_e32 v10, 0, v10
	v_max_f32_e32 v11, 0, v11
	v_mul_f32_e32 v8, v8, v8
	v_mul_f32_e32 v9, v9, v9
	v_mul_f32_e32 v10, v10, v10
	v_mul_f32_e32 v11, v11, v11
	v_cvt_pk_bf16_f32 v244, v8, v9
	v_cvt_pk_bf16_f32 v245, v10, v11
	ds_write_b64 v180, v[244:245]
	v_max_f32_e32 v12, 0, v12
	v_max_f32_e32 v13, 0, v13
	v_max_f32_e32 v14, 0, v14
	v_max_f32_e32 v15, 0, v15
	v_mul_f32_e32 v12, v12, v12
	v_mul_f32_e32 v13, v13, v13
	v_mul_f32_e32 v14, v14, v14
	v_mul_f32_e32 v15, v15, v15
	v_cvt_pk_bf16_f32 v246, v12, v13
	v_cvt_pk_bf16_f32 v247, v14, v15
	ds_write_b64 v181, v[246:247]
	ds_read_b128 v[0:3], v194
	ds_read_b128 v[4:7], v188 offset:1024
	v_max_f32_e32 v16, 0, v16
	v_max_f32_e32 v17, 0, v17
	v_max_f32_e32 v18, 0, v18
	v_max_f32_e32 v19, 0, v19
	v_mul_f32_e32 v16, v16, v16
	v_mul_f32_e32 v17, v17, v17
	v_mul_f32_e32 v18, v18, v18
	v_mul_f32_e32 v19, v19, v19
	v_cvt_pk_bf16_f32 v240, v16, v17
	v_cvt_pk_bf16_f32 v241, v18, v19
	ds_write_b64 v178, v[240:241]
	v_max_f32_e32 v20, 0, v20
	v_max_f32_e32 v21, 0, v21
	v_max_f32_e32 v22, 0, v22
	v_max_f32_e32 v23, 0, v23
	v_mul_f32_e32 v20, v20, v20
	v_mul_f32_e32 v21, v21, v21
	v_mul_f32_e32 v22, v22, v22
	v_mul_f32_e32 v23, v23, v23
	v_cvt_pk_bf16_f32 v242, v20, v21
	v_cvt_pk_bf16_f32 v243, v22, v23
	ds_write_b64 v179, v[242:243]
	v_max_f32_e32 v24, 0, v24
	v_max_f32_e32 v25, 0, v25
	v_max_f32_e32 v26, 0, v26
	v_max_f32_e32 v27, 0, v27
	v_mul_f32_e32 v24, v24, v24
	v_mul_f32_e32 v25, v25, v25
	v_mul_f32_e32 v26, v26, v26
	v_mul_f32_e32 v27, v27, v27
	v_cvt_pk_bf16_f32 v244, v24, v25
	v_cvt_pk_bf16_f32 v245, v26, v27
	ds_write_b64 v180, v[244:245]
	v_max_f32_e32 v28, 0, v28
	v_max_f32_e32 v29, 0, v29
	v_max_f32_e32 v30, 0, v30
	v_max_f32_e32 v31, 0, v31
	v_mul_f32_e32 v28, v28, v28
	v_mul_f32_e32 v29, v29, v29
	v_mul_f32_e32 v30, v30, v30
	v_mul_f32_e32 v31, v31, v31
	v_cvt_pk_bf16_f32 v246, v28, v29
	v_cvt_pk_bf16_f32 v247, v30, v31
	ds_write_b64 v181, v[246:247]
	ds_read_b128 v[16:19], v194
	ds_read_b128 v[20:23], v188 offset:1024
	s_waitcnt lgkmcnt(6)
	global_store_dwordx4 v195, v[0:3], s[38:39] nt
	s_add_u32 s38, s38, s40
	s_addc_u32 s39, s39, 0
	global_store_dwordx4 v195, v[4:7], s[38:39] nt
	s_add_u32 s38, s38, s40
	s_addc_u32 s39, s39, 0
	v_max_f32_e32 v32, 0, v32
	v_max_f32_e32 v33, 0, v33
	v_max_f32_e32 v34, 0, v34
	v_max_f32_e32 v35, 0, v35
	v_mul_f32_e32 v32, v32, v32
	v_mul_f32_e32 v33, v33, v33
	v_mul_f32_e32 v34, v34, v34
	v_mul_f32_e32 v35, v35, v35
	v_cvt_pk_bf16_f32 v240, v32, v33
	v_cvt_pk_bf16_f32 v241, v34, v35
	ds_write_b64 v178, v[240:241]
	v_max_f32_e32 v36, 0, v36
	v_max_f32_e32 v37, 0, v37
	v_max_f32_e32 v38, 0, v38
	v_max_f32_e32 v39, 0, v39
	v_mul_f32_e32 v36, v36, v36
	v_mul_f32_e32 v37, v37, v37
	v_mul_f32_e32 v38, v38, v38
	v_mul_f32_e32 v39, v39, v39
	v_cvt_pk_bf16_f32 v242, v36, v37
	v_cvt_pk_bf16_f32 v243, v38, v39
	ds_write_b64 v179, v[242:243]
	v_max_f32_e32 v40, 0, v40
	v_max_f32_e32 v41, 0, v41
	v_max_f32_e32 v42, 0, v42
	v_max_f32_e32 v43, 0, v43
	v_mul_f32_e32 v40, v40, v40
	v_mul_f32_e32 v41, v41, v41
	v_mul_f32_e32 v42, v42, v42
	v_mul_f32_e32 v43, v43, v43
	v_cvt_pk_bf16_f32 v244, v40, v41
	v_cvt_pk_bf16_f32 v245, v42, v43
	ds_write_b64 v180, v[244:245]
	v_max_f32_e32 v44, 0, v44
	v_max_f32_e32 v45, 0, v45
	v_max_f32_e32 v46, 0, v46
	v_max_f32_e32 v47, 0, v47
	v_mul_f32_e32 v44, v44, v44
	v_mul_f32_e32 v45, v45, v45
	v_mul_f32_e32 v46, v46, v46
	v_mul_f32_e32 v47, v47, v47
	v_cvt_pk_bf16_f32 v246, v44, v45
	v_cvt_pk_bf16_f32 v247, v46, v47
	ds_write_b64 v181, v[246:247]
	ds_read_b128 v[32:35], v194
	ds_read_b128 v[36:39], v188 offset:1024
	s_waitcnt lgkmcnt(6)
	global_store_dwordx4 v195, v[16:19], s[38:39] nt
	s_add_u32 s38, s38, s40
	s_addc_u32 s39, s39, 0
	global_store_dwordx4 v195, v[20:23], s[38:39] nt
	s_add_u32 s38, s38, s40
	s_addc_u32 s39, s39, 0
	v_max_f32_e32 v48, 0, v48
	v_max_f32_e32 v49, 0, v49
	v_max_f32_e32 v50, 0, v50
	v_max_f32_e32 v51, 0, v51
	v_mul_f32_e32 v48, v48, v48
	v_mul_f32_e32 v49, v49, v49
	v_mul_f32_e32 v50, v50, v50
	v_mul_f32_e32 v51, v51, v51
	v_cvt_pk_bf16_f32 v240, v48, v49
	v_cvt_pk_bf16_f32 v241, v50, v51
	ds_write_b64 v178, v[240:241]
	v_max_f32_e32 v52, 0, v52
	v_max_f32_e32 v53, 0, v53
	v_max_f32_e32 v54, 0, v54
	v_max_f32_e32 v55, 0, v55
	v_mul_f32_e32 v52, v52, v52
	v_mul_f32_e32 v53, v53, v53
	v_mul_f32_e32 v54, v54, v54
	v_mul_f32_e32 v55, v55, v55
	v_cvt_pk_bf16_f32 v242, v52, v53
	v_cvt_pk_bf16_f32 v243, v54, v55
	ds_write_b64 v179, v[242:243]
	v_max_f32_e32 v56, 0, v56
	v_max_f32_e32 v57, 0, v57
	v_max_f32_e32 v58, 0, v58
	v_max_f32_e32 v59, 0, v59
	v_mul_f32_e32 v56, v56, v56
	v_mul_f32_e32 v57, v57, v57
	v_mul_f32_e32 v58, v58, v58
	v_mul_f32_e32 v59, v59, v59
	v_cvt_pk_bf16_f32 v244, v56, v57
	v_cvt_pk_bf16_f32 v245, v58, v59
	ds_write_b64 v180, v[244:245]
	v_max_f32_e32 v60, 0, v60
	v_max_f32_e32 v61, 0, v61
	v_max_f32_e32 v62, 0, v62
	v_max_f32_e32 v63, 0, v63
	v_mul_f32_e32 v60, v60, v60
	v_mul_f32_e32 v61, v61, v61
	v_mul_f32_e32 v62, v62, v62
	v_mul_f32_e32 v63, v63, v63
	v_cvt_pk_bf16_f32 v246, v60, v61
	v_cvt_pk_bf16_f32 v247, v62, v63
	ds_write_b64 v181, v[246:247]
	ds_read_b128 v[48:51], v194
	ds_read_b128 v[52:55], v188 offset:1024
	s_waitcnt lgkmcnt(6)
; DI int crow(int r, int hf) { return (r & 3) + 8 * (r >> 2) + 4 * hf; }
;     ...
;           for (int r = 0; r < 16; ++r) {
;             const int row = m0_ + wm * 64 + i * 32 + crow(r, hf_), col = n0 + wn * 64 + j * 32 + l32_;
;             float v = acc[i][j][r];
;             if (mode == 1) { v = fmaxf(v, 0.f); v = v * v; }
;             if (V == 0 || v == 123456.789f) C[(size_t)row * ldc + col] = f2bf(v);
	global_store_dwordx4 v195, v[32:35], s[38:39] nt
	s_add_u32 s38, s38, s40
	s_addc_u32 s39, s39, 0
	global_store_dwordx4 v195, v[36:39], s[38:39] nt
	s_add_u32 s38, s38, s40
	s_addc_u32 s39, s39, 0
	v_max_f32_e32 v64, 0, v64
	v_max_f32_e32 v65, 0, v65
	v_max_f32_e32 v66, 0, v66
	v_max_f32_e32 v67, 0, v67
	v_mul_f32_e32 v64, v64, v64
	v_mul_f32_e32 v65, v65, v65
	v_mul_f32_e32 v66, v66, v66
	v_mul_f32_e32 v67, v67, v67
	v_cvt_pk_bf16_f32 v240, v64, v65
	v_cvt_pk_bf16_f32 v241, v66, v67
	ds_write_b64 v178, v[240:241]
	v_max_f32_e32 v68, 0, v68
	v_max_f32_e32 v69, 0, v69
	v_max_f32_e32 v70, 0, v70
	v_max_f32_e32 v71, 0, v71
	v_mul_f32_e32 v68, v68, v68
	v_mul_f32_e32 v69, v69, v69
	v_mul_f32_e32 v70, v70, v70
	v_mul_f32_e32 v71, v71, v71
	v_cvt_pk_bf16_f32 v242, v68, v69
	v_cvt_pk_bf16_f32 v243, v70, v71
	ds_write_b64 v179, v[242:243]
	v_max_f32_e32 v72, 0, v72
	v_max_f32_e32 v73, 0, v73
	v_max_f32_e32 v74, 0, v74
	v_max_f32_e32 v75, 0, v75
	v_mul_f32_e32 v72, v72, v72
	v_mul_f32_e32 v73, v73, v73
	v_mul_f32_e32 v74, v74, v74
	v_mul_f32_e32 v75, v75, v75
	v_cvt_pk_bf16_f32 v244, v72, v73
	v_cvt_pk_bf16_f32 v245, v74, v75
	ds_write_b64 v180, v[244:245]
	v_max_f32_e32 v76, 0, v76
	v_max_f32_e32 v77, 0, v77
	v_max_f32_e32 v78, 0, v78
	v_max_f32_e32 v79, 0, v79
	v_mul_f32_e32 v76, v76, v76
	v_mul_f32_e32 v77, v77, v77
	v_mul_f32_e32 v78, v78, v78
	v_mul_f32_e32 v79, v79, v79
	v_cvt_pk_bf16_f32 v246, v76, v77
	v_cvt_pk_bf16_f32 v247, v78, v79
	ds_write_b64 v181, v[246:247]
	ds_read_b128 v[64:67], v194
	ds_read_b128 v[68:71], v188 offset:1024
	s_waitcnt lgkmcnt(6)
	global_store_dwordx4 v195, v[48:51], s[38:39] nt
	s_add_u32 s38, s38, s40
	s_addc_u32 s39, s39, 0
	global_store_dwordx4 v195, v[52:55], s[38:39] nt
	s_add_u32 s38, s38, s40
	s_addc_u32 s39, s39, 0
	v_max_f32_e32 v80, 0, v80
	v_max_f32_e32 v81, 0, v81
	v_max_f32_e32 v82, 0, v82
	v_max_f32_e32 v83, 0, v83
	v_mul_f32_e32 v80, v80, v80
	v_mul_f32_e32 v81, v81, v81
	v_mul_f32_e32 v82, v82, v82
	v_mul_f32_e32 v83, v83, v83
	v_cvt_pk_bf16_f32 v240, v80, v81
	v_cvt_pk_bf16_f32 v241, v82, v83
	ds_write_b64 v178, v[240:241]
	v_max_f32_e32 v84, 0, v84
	v_max_f32_e32 v85, 0, v85
	v_max_f32_e32 v86, 0, v86
	v_max_f32_e32 v87, 0, v87
	v_mul_f32_e32 v84, v84, v84
	v_mul_f32_e32 v85, v85, v85
	v_mul_f32_e32 v86, v86, v86
	v_mul_f32_e32 v87, v87, v87
	v_cvt_pk_bf16_f32 v242, v84, v85
	v_cvt_pk_bf16_f32 v243, v86, v87
	ds_write_b64 v179, v[242:243]
	v_max_f32_e32 v88, 0, v88
	v_max_f32_e32 v89, 0, v89
	v_max_f32_e32 v90, 0, v90
	v_max_f32_e32 v91, 0, v91
	v_mul_f32_e32 v88, v88, v88
	v_mul_f32_e32 v89, v89, v89
	v_mul_f32_e32 v90, v90, v90
	v_mul_f32_e32 v91, v91, v91
	v_cvt_pk_bf16_f32 v244, v88, v89
	v_cvt_pk_bf16_f32 v245, v90, v91
	ds_write_b64 v180, v[244:245]
	v_max_f32_e32 v92, 0, v92
	v_max_f32_e32 v93, 0, v93
	v_max_f32_e32 v94, 0, v94
	v_max_f32_e32 v95, 0, v95
	v_mul_f32_e32 v92, v92, v92
	v_mul_f32_e32 v93, v93, v93
	v_mul_f32_e32 v94, v94, v94
	v_mul_f32_e32 v95, v95, v95
	v_cvt_pk_bf16_f32 v246, v92, v93
	v_cvt_pk_bf16_f32 v247, v94, v95
	ds_write_b64 v181, v[246:247]
	ds_read_b128 v[80:83], v194
	ds_read_b128 v[84:87], v188 offset:1024
	s_waitcnt lgkmcnt(6)
	global_store_dwordx4 v195, v[64:67], s[38:39] nt
	s_add_u32 s38, s38, s40
	s_addc_u32 s39, s39, 0
	global_store_dwordx4 v195, v[68:71], s[38:39] nt
	s_add_u32 s38, s38, s40
	s_addc_u32 s39, s39, 0
	v_max_f32_e32 v96, 0, v96
	v_max_f32_e32 v97, 0, v97
	v_max_f32_e32 v98, 0, v98
	v_max_f32_e32 v99, 0, v99
	v_mul_f32_e32 v96, v96, v96
	v_mul_f32_e32 v97, v97, v97
	v_mul_f32_e32 v98, v98, v98
	v_mul_f32_e32 v99, v99, v99
	v_cvt_pk_bf16_f32 v240, v96, v97
	v_cvt_pk_bf16_f32 v241, v98, v99
	ds_write_b64 v178, v[240:241]
	v_max_f32_e32 v100, 0, v100
	v_max_f32_e32 v101, 0, v101
	v_max_f32_e32 v102, 0, v102
	v_max_f32_e32 v103, 0, v103
	v_mul_f32_e32 v100, v100, v100
	v_mul_f32_e32 v101, v101, v101
	v_mul_f32_e32 v102, v102, v102
	v_mul_f32_e32 v103, v103, v103
	v_cvt_pk_bf16_f32 v242, v100, v101
	v_cvt_pk_bf16_f32 v243, v102, v103
	ds_write_b64 v179, v[242:243]
	v_max_f32_e32 v104, 0, v104
	v_max_f32_e32 v105, 0, v105
	v_max_f32_e32 v106, 0, v106
	v_max_f32_e32 v107, 0, v107
	v_mul_f32_e32 v104, v104, v104
	v_mul_f32_e32 v105, v105, v105
	v_mul_f32_e32 v106, v106, v106
	v_mul_f32_e32 v107, v107, v107
	v_cvt_pk_bf16_f32 v244, v104, v105
	v_cvt_pk_bf16_f32 v245, v106, v107
	ds_write_b64 v180, v[244:245]
	v_max_f32_e32 v108, 0, v108
	v_max_f32_e32 v109, 0, v109
	v_max_f32_e32 v110, 0, v110
	v_max_f32_e32 v111, 0, v111
	v_mul_f32_e32 v108, v108, v108
	v_mul_f32_e32 v109, v109, v109
	v_mul_f32_e32 v110, v110, v110
	v_mul_f32_e32 v111, v111, v111
	v_cvt_pk_bf16_f32 v246, v108, v109
	v_cvt_pk_bf16_f32 v247, v110, v111
	ds_write_b64 v181, v[246:247]
	ds_read_b128 v[96:99], v194
	ds_read_b128 v[100:103], v188 offset:1024
	s_waitcnt lgkmcnt(6)
	global_store_dwordx4 v195, v[80:83], s[38:39] nt
	s_add_u32 s38, s38, s40
	s_addc_u32 s39, s39, 0
	global_store_dwordx4 v195, v[84:87], s[38:39] nt
	s_add_u32 s38, s38, s40
	s_addc_u32 s39, s39, 0
	v_max_f32_e32 v112, 0, v112
	v_max_f32_e32 v113, 0, v113
	v_max_f32_e32 v114, 0, v114
	v_max_f32_e32 v115, 0, v115
	v_mul_f32_e32 v112, v112, v112
	v_mul_f32_e32 v113, v113, v113
	v_mul_f32_e32 v114, v114, v114
	v_mul_f32_e32 v115, v115, v115
	v_cvt_pk_bf16_f32 v240, v112, v113
	v_cvt_pk_bf16_f32 v241, v114, v115
	ds_write_b64 v178, v[240:241]
	v_max_f32_e32 v116, 0, v116
	v_max_f32_e32 v117, 0, v117
	v_max_f32_e32 v118, 0, v118
	v_max_f32_e32 v119, 0, v119
	v_mul_f32_e32 v116, v116, v116
	v_mul_f32_e32 v117, v117, v117
	v_mul_f32_e32 v118, v118, v118
	v_mul_f32_e32 v119, v119, v119
	v_cvt_pk_bf16_f32 v242, v116, v117
	v_cvt_pk_bf16_f32 v243, v118, v119
	ds_write_b64 v179, v[242:243]
	v_max_f32_e32 v120, 0, v120
	v_max_f32_e32 v121, 0, v121
	v_max_f32_e32 v122, 0, v122
	v_max_f32_e32 v123, 0, v123
	v_mul_f32_e32 v120, v120, v120
	v_mul_f32_e32 v121, v121, v121
	v_mul_f32_e32 v122, v122, v122
	v_mul_f32_e32 v123, v123, v123
	v_cvt_pk_bf16_f32 v244, v120, v121
	v_cvt_pk_bf16_f32 v245, v122, v123
	ds_write_b64 v180, v[244:245]
	v_max_f32_e32 v124, 0, v124
	v_max_f32_e32 v125, 0, v125
	v_max_f32_e32 v126, 0, v126
	v_max_f32_e32 v127, 0, v127
	v_mul_f32_e32 v124, v124, v124
	v_mul_f32_e32 v125, v125, v125
	v_mul_f32_e32 v126, v126, v126
	v_mul_f32_e32 v127, v127, v127
	v_cvt_pk_bf16_f32 v246, v124, v125
	v_cvt_pk_bf16_f32 v247, v126, v127
	ds_write_b64 v181, v[246:247]
	ds_read_b128 v[112:115], v194
	ds_read_b128 v[116:119], v188 offset:1024
	s_waitcnt lgkmcnt(6)
	global_store_dwordx4 v195, v[96:99], s[38:39] nt
	s_add_u32 s38, s38, s40
	s_addc_u32 s39, s39, 0
	global_store_dwordx4 v195, v[100:103], s[38:39] nt
	s_add_u32 s38, s38, s40
	s_addc_u32 s39, s39, 0
	s_waitcnt lgkmcnt(0)
	global_store_dwordx4 v195, v[112:115], s[38:39] nt
	s_add_u32 s38, s38, s40
	s_addc_u32 s39, s39, 0
	global_store_dwordx4 v195, v[116:119], s[38:39] nt
;     ...
;   for (int lt = blockIdx.x >> 3; lt < 16 * nN; lt += gridDim.x >> 3) {
;     int mt, nt; tile_map(lt, 16, nN, 8, 4, mt, nt);
;     const int m0 = mt * 256, n0 = nt * 256;
;     gemm_tile<V>(A + (size_t)m0 * lda, lda, K / 64, nullptr, 0, 0, Wt + (size_t)n0 * ldb, ldb, smem, [&](f32x16(&acc)[2][2], int moff) {
.Lgm_epi_done:
	s_add_u32 s28, s28, s30
	s_cmp_lt_u32 s28, s29
	s_cbranch_scc1 .Lgm_tile
	s_waitcnt vmcnt(0) lgkmcnt(0)
	s_cmp_lt_u32 s15, 4
	s_cbranch_scc0 .Lgm_pp_trail
	s_barrier
.Lgm_pp_trail:
.LBB0_882:
	v_readlane_b32 s60, v254, 21
	v_readlane_b32 s61, v254, 22
	v_readlane_b32 s56, v254, 14
	v_readlane_b32 s38, v254, 16
	v_readlane_b32 s58, v254, 18
	v_readlane_b32 s40, v254, 19
	v_readlane_b32 s41, v254, 20
	s_mov_b32 s59, 0x800000
	s_movk_i32 s53, 0x104
	v_readlane_b32 s57, v254, 15
	v_readlane_b32 s39, v254, 17
	s_movk_i32 s62, 0x1000
	s_branch .LBB0_1084
